# ofprep_norm: second row's gain/scale/shift loads issued in the same batch as the first row's
# speedup vs baseline: 1.0052x; 1.0005x over previous
.LBB0_1575:
	s_or_b64 exec, exec, s[0:1]
	s_nop 0
	v_mul_f32_e32 v32, v29, v29
	v_mul_f32_e32 v33, v25, v25
	v_fmac_f32_e32 v32, v28, v28
	v_fmac_f32_e32 v33, v24, v24
	v_fmac_f32_e32 v32, v30, v30
	v_fmac_f32_e32 v33, v26, v26
	v_fmac_f32_e32 v32, v31, v31
	v_fmac_f32_e32 v33, v27, v27
	v_add_f32_e32 v32, v32, v33
	v_mul_f32_e32 v33, v21, v21
	v_fmac_f32_e32 v33, v20, v20
	v_fmac_f32_e32 v33, v22, v22
	v_fmac_f32_e32 v33, v23, v23
	v_add_f32_e32 v32, v32, v33
	v_mul_f32_e32 v33, v17, v17
	v_fmac_f32_e32 v33, v16, v16
	v_fmac_f32_e32 v33, v18, v18
	v_fmac_f32_e32 v33, v19, v19
	v_add_f32_e32 v32, v32, v33
	v_mul_f32_e32 v33, v13, v13
	v_mul_f32_e32 v34, v9, v9
	v_fmac_f32_e32 v33, v12, v12
	v_fmac_f32_e32 v34, v8, v8
	v_fmac_f32_e32 v33, v14, v14
	v_fmac_f32_e32 v34, v10, v10
	v_fmac_f32_e32 v33, v15, v15
	v_fmac_f32_e32 v34, v11, v11
	v_add_f32_e32 v33, v33, v34
	v_mul_f32_e32 v34, v5, v5
	v_fmac_f32_e32 v34, v4, v4
	v_fmac_f32_e32 v34, v6, v6
	v_fmac_f32_e32 v34, v7, v7
	v_add_f32_e32 v33, v33, v34
	v_mul_f32_e32 v34, v1, v1
	v_fmac_f32_e32 v34, v0, v0
	v_fmac_f32_e32 v34, v2, v2
	v_fmac_f32_e32 v34, v3, v3
	v_add_f32_e32 v33, v33, v34
	ds_bpermute_b32 v34, v98, v32
	s_mov_b64 s[0:1], 0x4000
	global_load_dwordx4 v[42:45], v[74:75], off offset:16
	global_load_dwordx4 v[46:49], v[74:75], off
	v_lshlrev_b64 v[38:39], 11, v[84:85]
	s_waitcnt lgkmcnt(0)
	v_add_f32_e32 v32, v32, v34
	ds_bpermute_b32 v34, v98, v33
	s_waitcnt lgkmcnt(0)
	v_add_f32_e32 v33, v33, v34
	ds_bpermute_b32 v34, v99, v32
	s_waitcnt lgkmcnt(0)
	v_add_f32_e32 v32, v32, v34
	ds_bpermute_b32 v34, v99, v33
	s_waitcnt lgkmcnt(0)
	v_add_f32_e32 v33, v33, v34
	ds_bpermute_b32 v34, v97, v32
	s_waitcnt lgkmcnt(0)
	v_add_f32_e32 v32, v32, v34
	ds_bpermute_b32 v34, v97, v33
	s_waitcnt lgkmcnt(0)
	v_add_f32_e32 v33, v33, v34
	ds_bpermute_b32 v34, v96, v32
	s_waitcnt lgkmcnt(0)
	v_add_f32_e32 v32, v32, v34
	ds_bpermute_b32 v34, v96, v33
	s_waitcnt lgkmcnt(0)
	v_add_f32_e32 v33, v33, v34
	ds_bpermute_b32 v34, v95, v32
	s_waitcnt lgkmcnt(0)
	v_add_f32_e32 v32, v32, v34
	ds_bpermute_b32 v34, v95, v33
	s_waitcnt lgkmcnt(0)
	v_add_f32_e32 v33, v33, v34
	ds_bpermute_b32 v34, v94, v32
	ds_bpermute_b32 v40, v94, v33
	s_waitcnt lgkmcnt(0)
	v_add_f32_e32 v32, v32, v34
	v_fmamk_f32 v32, v32, 0x3a800000, v191
	v_cmp_gt_f32_e32 vcc, s81, v32
	v_mul_f32_e32 v36, 0x4b800000, v32
	v_min_i32_e32 v34, 0x8000, v84
	v_cndmask_b32_e32 v32, v32, v36, vcc
	v_ashrrev_i32_e32 v34, 12, v34
	v_rsq_f32_e32 v32, v32
	v_mul_i32_i24_e32 v34, 9, v34
	v_ashrrev_i32_e32 v35, 31, v34
	v_lshlrev_b64 v[34:35], 12, v[34:35]
	v_mul_f32_e32 v36, 0x45800000, v32
	v_lshl_add_u64 v[54:55], v[78:79], 0, v[34:35]
	v_cndmask_b32_e32 v32, v32, v36, vcc
	v_lshl_add_u64 v[36:37], v[54:55], 0, s[0:1]
	s_mov_b64 s[0:1], 0x3000
	v_lshl_add_u64 v[34:35], v[54:55], 0, s[0:1]
	s_movk_i32 s0, 0x4000
	v_add_co_u32_e32 v50, vcc, s0, v54
	s_movk_i32 s0, 0x3000
	s_nop 0
	v_addc_co_u32_e32 v51, vcc, 0, v55, vcc
	v_add_co_u32_e32 v54, vcc, s0, v54
	flat_load_dwordx4 v[50:53], v[50:51]
	s_nop 0
	v_addc_co_u32_e32 v55, vcc, 0, v55, vcc
	flat_load_dwordx4 v[54:57], v[54:55]
	global_load_dwordx4 v[112:115], v[36:37], off offset:16
	global_load_dwordx4 v[116:119], v[34:35], off offset:16
	global_load_dwordx4 v[120:123], v[76:77], off offset:16
	global_load_dwordx4 v[124:127], v[76:77], off
	global_load_dwordx4 v[128:131], v[36:37], off offset:2048
	global_load_dwordx4 v[132:135], v[34:35], off offset:2048
	global_load_dwordx4 v[136:139], v[36:37], off offset:2064
	global_load_dwordx4 v[140:143], v[34:35], off offset:2064
	v_min_i32_e32 v200, 0x8000, v82
	v_ashrrev_i32_e32 v200, 12, v200
	v_mul_i32_i24_e32 v200, 9, v200
	v_ashrrev_i32_e32 v201, 31, v200
	v_lshlrev_b64 v[200:201], 12, v[200:201]
	v_lshl_add_u64 v[200:201], v[78:79], 0, v[200:201]
	s_mov_b64 s[98:99], 0x4000
	v_lshl_add_u64 v[202:203], v[200:201], 0, s[98:99]
	s_mov_b64 s[98:99], 0x3000
	v_lshl_add_u64 v[204:205], v[200:201], 0, s[98:99]
	global_load_dwordx4 v[224:227], v[74:75], off offset:16
	global_load_dwordx4 v[228:231], v[74:75], off
	global_load_dwordx4 v[232:235], v[202:203], off
	global_load_dwordx4 v[236:239], v[204:205], off
	global_load_dwordx4 v[144:147], v[202:203], off offset:16
	global_load_dwordx4 v[148:151], v[204:205], off offset:16
	global_load_dwordx4 v[152:155], v[76:77], off offset:16
	global_load_dwordx4 v[156:159], v[76:77], off
	global_load_dwordx4 v[160:163], v[202:203], off offset:2048
	global_load_dwordx4 v[164:167], v[204:205], off offset:2048
	global_load_dwordx4 v[168:171], v[202:203], off offset:2064
	global_load_dwordx4 v[172:175], v[204:205], off offset:2064
	v_pk_mul_f32 v[30:31], v[30:31], v[32:33] op_sel_hi:[1,0]
	v_pk_mul_f32 v[28:29], v[28:29], v[32:33] op_sel_hi:[1,0]
	s_waitcnt vmcnt(0)
	v_pk_mul_f32 v[30:31], v[48:49], v[30:31]
	v_pk_mul_f32 v[28:29], v[46:47], v[28:29]
	v_pk_mul_f32 v[26:27], v[26:27], v[32:33] op_sel_hi:[1,0]
	v_pk_mul_f32 v[24:25], v[24:25], v[32:33] op_sel_hi:[1,0]
	v_pk_mul_f32 v[26:27], v[44:45], v[26:27]
	v_pk_mul_f32 v[24:25], v[42:43], v[24:25]
	v_pk_mul_f32 v[22:23], v[22:23], v[32:33] op_sel_hi:[1,0]
	v_pk_mul_f32 v[20:21], v[20:21], v[32:33] op_sel_hi:[1,0]
	v_pk_mul_f32 v[18:19], v[18:19], v[32:33] op_sel_hi:[1,0]
	v_pk_mul_f32 v[16:17], v[16:17], v[32:33] op_sel_hi:[1,0]
	s_mov_b32 s0, 0x8800
	v_cmp_gt_i32_e32 vcc, s0, v82
	s_waitcnt lgkmcnt(0)
	v_pk_add_f32 v[46:47], v[52:53], 1.0 op_sel_hi:[1,0]
	v_pk_add_f32 v[48:49], v[50:51], 1.0 op_sel_hi:[1,0]
	v_pk_fma_f32 v[50:51], v[46:47], v[30:31], v[56:57]
	v_pk_fma_f32 v[52:53], v[48:49], v[28:29], v[54:55]
	s_nop 1
	v_mov_b64_e32 v[28:29], v[112:113]
	v_mov_b64_e32 v[30:31], v[114:115]
	s_nop 1
	v_mov_b64_e32 v[46:47], v[116:117]
	v_mov_b64_e32 v[48:49], v[118:119]
	s_waitcnt vmcnt(0) lgkmcnt(0)
	v_pk_add_f32 v[30:31], v[30:31], 1.0 op_sel_hi:[1,0]
	v_pk_add_f32 v[28:29], v[28:29], 1.0 op_sel_hi:[1,0]
	v_pk_fma_f32 v[30:31], v[30:31], v[26:27], v[48:49]
	v_pk_fma_f32 v[26:27], v[28:29], v[24:25], v[46:47]
	v_cvt_pk_bf16_f32 v24, v52, v53
	v_cvt_pk_bf16_f32 v25, v50, v51
	v_cvt_pk_bf16_f32 v26, v26, v27
	v_cvt_pk_bf16_f32 v27, v30, v31
	v_lshl_add_u64 v[28:29], v[80:81], 0, v[38:39]
	flat_store_dwordx4 v[28:29], v[24:27]
	s_nop 1
	v_mov_b64_e32 v[24:25], v[120:121]
	v_mov_b64_e32 v[26:27], v[122:123]
	s_nop 0
	s_nop 1
	v_mov_b64_e32 v[42:43], v[124:125]
	v_mov_b64_e32 v[44:45], v[126:127]
	s_nop 1
	v_mov_b64_e32 v[46:47], v[128:129]
	v_mov_b64_e32 v[48:49], v[130:131]
	s_nop 1
	v_mov_b64_e32 v[50:51], v[132:133]
	v_mov_b64_e32 v[52:53], v[134:135]
	s_waitcnt vmcnt(0)
	v_pk_mul_f32 v[16:17], v[24:25], v[16:17]
	v_pk_mul_f32 v[20:21], v[42:43], v[20:21]
	v_pk_mul_f32 v[22:23], v[44:45], v[22:23]
	s_waitcnt lgkmcnt(0)
	v_pk_add_f32 v[30:31], v[48:49], 1.0 op_sel_hi:[1,0]
	v_pk_add_f32 v[38:39], v[46:47], 1.0 op_sel_hi:[1,0]
	v_pk_fma_f32 v[30:31], v[30:31], v[22:23], v[52:53]
	v_pk_fma_f32 v[38:39], v[38:39], v[20:21], v[50:51]
	s_nop 1
	v_mov_b64_e32 v[20:21], v[136:137]
	v_mov_b64_e32 v[22:23], v[138:139]
	s_nop 0
	s_nop 1
	v_mov_b64_e32 v[34:35], v[140:141]
	v_mov_b64_e32 v[36:37], v[142:143]
	v_pk_mul_f32 v[18:19], v[26:27], v[18:19]
	s_waitcnt vmcnt(0) lgkmcnt(0)
	v_pk_add_f32 v[22:23], v[22:23], 1.0 op_sel_hi:[1,0]
	v_pk_add_f32 v[20:21], v[20:21], 1.0 op_sel_hi:[1,0]
	v_pk_fma_f32 v[22:23], v[18:19], v[22:23], v[36:37]
	v_pk_fma_f32 v[18:19], v[16:17], v[20:21], v[34:35]
	v_cvt_pk_bf16_f32 v16, v38, v39
	v_cvt_pk_bf16_f32 v17, v30, v31
	v_cvt_pk_bf16_f32 v18, v18, v19
	v_cvt_pk_bf16_f32 v19, v22, v23
	flat_store_dwordx4 v[28:29], v[16:19] offset:1024
	s_and_saveexec_b64 s[0:1], vcc
	s_cbranch_execz .LBB0_1572
	v_min_i32_e32 v16, 0x8000, v82
	v_ashrrev_i32_e32 v16, 12, v16
	v_mul_i32_i24_e32 v16, 9, v16
	v_add_f32_e32 v20, v33, v40
	v_ashrrev_i32_e32 v17, 31, v16
	v_lshlrev_b64 v[18:19], 12, v[16:17]
	v_fmamk_f32 v16, v20, 0x3a800000, v191
	v_cmp_gt_f32_e32 vcc, s81, v16
	v_mul_f32_e32 v17, 0x4b800000, v16
	v_lshl_add_u64 v[34:35], v[78:79], 0, v[18:19]
	v_cndmask_b32_e32 v16, v16, v17, vcc
	v_rsq_f32_e32 v16, v16
	s_movk_i32 s30, 0x4000
	s_mov_b64 s[42:43], 0x4000
	v_lshl_add_u64 v[20:21], v[34:35], 0, s[42:43]
	v_mul_f32_e32 v17, 0x45800000, v16
	v_cndmask_b32_e32 v16, v16, v17, vcc
	v_add_co_u32_e32 v30, vcc, s30, v34
	s_mov_b64 s[42:43], 0x3000
	s_nop 0
	v_addc_co_u32_e32 v31, vcc, 0, v35, vcc
	s_movk_i32 s30, 0x3000
	v_lshl_add_u64 v[18:19], v[34:35], 0, s[42:43]
	v_add_co_u32_e32 v34, vcc, s30, v34
	v_mov_b64_e32 v[22:23], v[224:225]
	v_mov_b64_e32 v[24:25], v[226:227]
	v_mov_b64_e32 v[26:27], v[228:229]
	v_mov_b64_e32 v[28:29], v[230:231]
	v_addc_co_u32_e32 v35, vcc, 0, v35, vcc
	v_mov_b64_e32 v[30:31], v[232:233]
	v_mov_b64_e32 v[32:33], v[234:235]
	v_pk_mul_f32 v[14:15], v[14:15], v[16:17] op_sel_hi:[1,0]
	v_mov_b64_e32 v[34:35], v[236:237]
	v_mov_b64_e32 v[36:37], v[238:239]
	v_pk_mul_f32 v[12:13], v[12:13], v[16:17] op_sel_hi:[1,0]
	v_pk_mul_f32 v[10:11], v[10:11], v[16:17] op_sel_hi:[1,0]
	v_pk_mul_f32 v[8:9], v[8:9], v[16:17] op_sel_hi:[1,0]
	v_lshlrev_b64 v[38:39], 11, v[82:83]
	v_pk_mul_f32 v[6:7], v[6:7], v[16:17] op_sel_hi:[1,0]
	v_pk_mul_f32 v[4:5], v[4:5], v[16:17] op_sel_hi:[1,0]
	v_pk_mul_f32 v[2:3], v[2:3], v[16:17] op_sel_hi:[1,0]
	v_pk_mul_f32 v[0:1], v[0:1], v[16:17] op_sel_hi:[1,0]
	s_waitcnt vmcnt(0)
	v_pk_mul_f32 v[8:9], v[8:9], v[22:23]
	v_pk_mul_f32 v[12:13], v[12:13], v[26:27]
	v_pk_mul_f32 v[14:15], v[14:15], v[28:29]
	v_pk_mul_f32 v[10:11], v[10:11], v[24:25]
	s_waitcnt lgkmcnt(0)
	v_pk_add_f32 v[26:27], v[32:33], 1.0 op_sel_hi:[1,0]
	v_pk_add_f32 v[28:29], v[30:31], 1.0 op_sel_hi:[1,0]
	v_pk_fma_f32 v[30:31], v[14:15], v[26:27], v[36:37]
	v_pk_fma_f32 v[32:33], v[12:13], v[28:29], v[34:35]
	s_nop 1
	v_mov_b64_e32 v[12:13], v[144:145]
	v_mov_b64_e32 v[14:15], v[146:147]
	s_nop 1
	v_mov_b64_e32 v[26:27], v[148:149]
	v_mov_b64_e32 v[28:29], v[150:151]
	s_waitcnt vmcnt(0) lgkmcnt(0)
	v_pk_add_f32 v[14:15], v[14:15], 1.0 op_sel_hi:[1,0]
	v_pk_add_f32 v[12:13], v[12:13], 1.0 op_sel_hi:[1,0]
	v_pk_fma_f32 v[14:15], v[10:11], v[14:15], v[28:29]
	v_pk_fma_f32 v[10:11], v[8:9], v[12:13], v[26:27]
	v_cvt_pk_bf16_f32 v8, v32, v33
	v_cvt_pk_bf16_f32 v9, v30, v31
	v_cvt_pk_bf16_f32 v10, v10, v11
	v_cvt_pk_bf16_f32 v11, v14, v15
	v_lshl_add_u64 v[30:31], v[80:81], 0, v[38:39]
	flat_store_dwordx4 v[30:31], v[8:11]
	s_nop 1
	v_mov_b64_e32 v[8:9], v[152:153]
	v_mov_b64_e32 v[10:11], v[154:155]
	s_nop 0
	s_nop 1
	v_mov_b64_e32 v[12:13], v[156:157]
	v_mov_b64_e32 v[14:15], v[158:159]
	s_nop 1
	v_mov_b64_e32 v[22:23], v[160:161]
	v_mov_b64_e32 v[24:25], v[162:163]
	s_nop 1
	v_mov_b64_e32 v[26:27], v[164:165]
	v_mov_b64_e32 v[28:29], v[166:167]
	s_waitcnt vmcnt(0)
	v_pk_mul_f32 v[0:1], v[0:1], v[8:9]
	v_pk_mul_f32 v[4:5], v[4:5], v[12:13]
	v_pk_mul_f32 v[6:7], v[6:7], v[14:15]
	s_waitcnt lgkmcnt(0)
	v_pk_add_f32 v[12:13], v[24:25], 1.0 op_sel_hi:[1,0]
	v_pk_add_f32 v[14:15], v[22:23], 1.0 op_sel_hi:[1,0]
	v_pk_fma_f32 v[22:23], v[6:7], v[12:13], v[28:29]
	v_pk_fma_f32 v[24:25], v[4:5], v[14:15], v[26:27]
	s_nop 1
	v_mov_b64_e32 v[4:5], v[168:169]
	v_mov_b64_e32 v[6:7], v[170:171]
	s_nop 1
	v_mov_b64_e32 v[12:13], v[172:173]
	v_mov_b64_e32 v[14:15], v[174:175]
	v_pk_mul_f32 v[2:3], v[2:3], v[10:11]
	s_waitcnt vmcnt(0) lgkmcnt(0)
	v_pk_add_f32 v[6:7], v[6:7], 1.0 op_sel_hi:[1,0]
	v_pk_add_f32 v[4:5], v[4:5], 1.0 op_sel_hi:[1,0]
	v_pk_fma_f32 v[6:7], v[2:3], v[6:7], v[14:15]
	v_pk_fma_f32 v[2:3], v[0:1], v[4:5], v[12:13]
	v_cvt_pk_bf16_f32 v0, v24, v25
	v_cvt_pk_bf16_f32 v1, v22, v23
	v_cvt_pk_bf16_f32 v2, v2, v3
	v_cvt_pk_bf16_f32 v3, v6, v7
	flat_store_dwordx4 v[30:31], v[0:3] offset:1024
	s_branch .LBB0_1572
